# attention item boundary: next item's Q, first K/V tile and sink loaded behind the epilogue's gate loads (before its stores); next prologue waits vmcnt(8) instead of vmcnt(0)
# baseline (speedup 1.0000x reference)
; DI int v_st(int k, int c) { const int kk = (k & ~0xC) | ((k & 4) << 1) | ((k & 8) >> 1); return ((kk >> 3) * 4 + (c >> 5)) * 512 + ((kk & 7) * 32 + (c & 31)) * 2; }
; DI int v_rd_base(int lane) { return ((lane & 3) << 3) | (((lane >> 2) & 3) << 6) | (((lane >> 4) & 1) << 5) | (((lane >> 5) & 1) << 8); }
; DI void attn_item(const bf16_t* __restrict__ Qw_, const bf16_t* __restrict__ Kh, const bf16_t* __restrict__ Vh, const bf16_t* Gw, bf16_t* Ow,
;                   int NT, int kt0, int qw, float sinkv, char* lds) {
;     const int tid = threadIdx.x, wid = __builtin_amdgcn_readfirstlane(tid >> 6), lane = tid & 63, r32 = lane & 31, hi = lane >> 5;
;     char* V_lds = lds; char* K_lds = lds + 2 * SHM_V;
;     float* wsp = (float*)(lds + 2 * SHM_V + 2 * SHM_K) + wid * 64; float* li_l = wsp; float* al_l = wsp + 32;
;     float m_reg = sinkv * (1.f / SCALE), l_reg = 1.f; f32x16 o[4]; bf16x8 qr[8];
; #pragma unroll
;     for (int d = 0; d < 4; ++d)
; #pragma unroll
;         for (int r = 0; r < 16; ++r) o[d][r] = 0.f;
;     const bf16_t* Qw = Qw_ + (size_t)r32 * LDK + hi * 8;
; #pragma unroll
;     for (int d0 = 0; d0 < 8; ++d0) qr[d0] = *(const bf16x8*)(Qw + d0 * 16);
;     const int sr = tid >> 4, sc = (tid & 15) * 8, vst0 = v_st(sr, sc), vst1 = v_st(32 + sr, sc);
;     const int vb0 = (int)(uintptr_t)V_lds + v_rd_base(lane);
; DI void phase_att(const Params& p, unsigned char* shm) {
;     const int wid = __builtin_amdgcn_readfirstlane(threadIdx.x >> 6);
;     const bf16_t* Z = (const bf16_t*)(p.ws + WS_ZQKV); const bf16_t* GA = (const bf16_t*)(p.ws + WS_ZGA); bf16_t* YB = (bf16_t*)(p.ws + WS_YB);
;     for (int it = blockIdx.x; it < 1024; it += gridDim.x) {
;         const int hp = it & 1, g = (it >> 1) & 3, n = it >> 3;
;         const int head = g * 4 + hp * 2 + (wid >> 2), qw = 32 * (wid & 3);
;         const int kfirst = n == 0 ? 0 : (n - 1) * 128, NT = (n == 0 || n == 127) ? 4 : 6, kt0 = kfirst - n * 128;
.LBB0_234:
	s_bitcmp0_b32 s4, 1
	s_cbranch_scc1 .LBB0_266
	s_cmpk_gt_i32 s2, 0x3ff
	v_readfirstlane_b32 s6, v202
	s_cbranch_scc1 .LBB0_265
	v_lshrrev_b32_e32 v180, 4, v202
	s_load_dwordx2 s[4:5], s[0:1], 0x80
	s_load_dwordx2 s[8:9], s[0:1], 0x50
	s_waitcnt vmcnt(0)
	v_add_u32_e32 v10, 32, v180
	v_and_b32_e32 v5, 48, v180
	v_lshrrev_b32_e32 v6, 3, v202
	v_and_b32_e32 v11, 0x70, v10
	v_lshlrev_b32_e32 v12, 1, v10
	v_lshlrev_b32_e32 v3, 3, v202
	v_and_or_b32 v5, v6, 8, v5
	v_and_or_b32 v11, v12, 8, v11
	v_and_b32_e32 v4, 0x78, v3
	v_lshrrev_b32_e32 v5, 1, v5
	v_bfe_u32 v6, v3, 5, 2
	v_bfe_u32 v7, v202, 4, 2
	v_lshrrev_b32_e32 v11, 1, v11
	s_waitcnt lgkmcnt(0)
	s_add_u32 s11, s4, 0x8000000
	v_or_b32_e32 v5, v5, v6
	v_and_or_b32 v7, v203, 4, v7
	v_lshlrev_b32_e32 v8, 1, v4
	v_or_b32_e32 v6, v11, v6
	s_addc_u32 s22, s5, 0
	v_lshlrev_b32_e32 v5, 9, v5
	v_lshlrev_b32_e32 v7, 6, v7
	v_and_b32_e32 v9, 48, v8
	v_lshlrev_b32_e32 v6, 9, v6
	s_add_u32 s23, s4, 0xe000000
	v_or3_b32 v5, v5, v7, v9
	v_or3_b32 v7, v6, v7, v9
	v_lshlrev_b32_e32 v9, 4, v202
	v_lshlrev_b32_e32 v11, 1, v202
	s_addc_u32 s30, s5, 0
	s_lshr_b32 s31, s6, 8
	s_lshr_b32 s6, s6, 1
	v_bfe_u32 v0, v202, 5, 1
	v_and_b32_e32 v6, 0xc0, v9
	v_and_b32_e32 v11, 32, v11
	v_and_b32_e32 v3, 0x118, v3
	v_and_b32_e32 v188, 31, v202
	s_and_b32 s34, s6, 0x60
	v_or3_b32 v3, v11, v6, v3
	v_lshlrev_b32_e32 v11, 8, v180
	v_and_b32_e32 v12, 0x70, v202
	v_lshlrev_b32_e32 v10, 8, v10
	v_lshlrev_b32_e32 v191, 4, v0
	s_cmp_lg_u32 0, -1
	v_bitop3_b32 v11, v8, v11, v12 bitop3:0xde
	v_bitop3_b32 v13, v8, v10, v12 bitop3:0xde
	v_lshlrev_b32_e32 v8, 8, v188
	v_and_b32_e32 v9, 0x70, v9
	v_or_b32_e32 v10, 32, v191
	s_cselect_b32 s10, 0, 0
	v_bitop3_b32 v18, v10, v8, v9 bitop3:0xde
	v_or_b32_e32 v10, 64, v191
	v_add_u32_e32 v190, s10, v3
	v_bitop3_b32 v19, v10, v8, v9 bitop3:0xde
	v_or_b32_e32 v10, 0x60, v191
	v_lshlrev_b32_e32 v193, 2, v0
	s_addk_i32 s10, 0x4000
	v_lshlrev_b32_e32 v2, 3, v0
	v_bitop3_b32 v20, v10, v8, v9 bitop3:0xde
	v_or_b32_e32 v10, 0x80, v191
	v_add_u32_e32 v194, s10, v3
	v_mul_u32_u24_e32 v196, 0x440, v0
	v_or_b32_e32 v0, 1, v193
	s_movk_i32 s39, 0x110
	v_mov_b32_e32 v3, 0x990
	v_bitop3_b32 v21, v10, v8, v9 bitop3:0xde
	v_or_b32_e32 v10, 0xa0, v191
	v_mul_u32_u24_e32 v197, 0x110, v0
	v_mad_u32_u24 v198, v0, s39, v3
	v_sub_u32_e32 v0, v193, v188
	v_mul_u32_u24_e32 v6, 0xc00, v180
	v_bitop3_b32 v22, v10, v8, v9 bitop3:0xde
	v_or_b32_e32 v10, 0xc0, v191
	v_subrev_u32_e32 v199, s34, v0
	v_and_b32_e32 v0, 15, v202
	v_mov_b32_e32 v1, 0
	v_or_b32_e32 v4, v6, v4
	v_bitop3_b32 v23, v10, v8, v9 bitop3:0xde
	v_or_b32_e32 v10, 0xe0, v191
	v_lshlrev_b32_e32 v0, 4, v0
	v_and_b32_e32 v189, 63, v202
	v_add_u32_e32 v6, 0x18000, v4
	v_bitop3_b32 v15, v191, v8, v9 bitop3:0xde
	v_bitop3_b32 v9, v10, v8, v9 bitop3:0xde
	v_or_b32_e32 v192, s34, v188
	v_add_u32_e32 v8, 0x30000, v4
	v_add_u32_e32 v10, 0x48000, v4
	v_add_u32_e32 v12, 0x78000, v4
	v_add_u32_e32 v14, 0x60000, v4
	v_lshl_add_u64 v[16:17], s[4:5], 0, v[0:1]
	s_mov_b64 s[4:5], 0x81b1400
	s_movk_i32 s35, 0x1800
	v_mul_u32_u24_e32 v178, 0x1800, v188
	v_mov_b32_e32 v179, v1
	s_mov_b32 s36, 0x18000
	s_or_b32 s37, s6, 0xffffff9f
	v_cmp_gt_u32_e64 s[6:7], 32, v189
	s_movk_i32 s38, 0x4000
	v_sub_u32_e32 v195, v193, v192
	s_sub_i32 s40, 0, s34
	v_lshl_add_u64 v[182:183], v[16:17], 0, s[4:5]
	v_mov_b32_e32 v181, v1
	v_lshlrev_b32_e32 v184, 1, v2
	v_lshlrev_b32_e32 v200, 1, v4
	v_lshlrev_b32_e32 v201, 1, v6
	s_movk_i32 s41, 0x101
	s_mov_b32 s42, 0x10000
	s_mov_b32 s43, 0x413504f3
	s_mov_b32 s44, 0x42b504f3
	s_mov_b32 s10, 0x3e0293ee
	v_lshlrev_b32_e32 v204, 1, v8
	v_lshlrev_b32_e32 v205, 1, v10
	v_lshlrev_b32_e32 v206, 1, v12
	v_lshlrev_b32_e32 v207, 1, v14
	s_mov_b32 s45, 0xfff70000
	s_mov_b32 s46, 0xfffa0000
	s_mov_b64 s[12:13], 0xc0000
	s_mov_b32 s47, 0x8000
	s_mov_b32 s48, 0xc000
	s_mov_b32 s49, 0x14000
	s_mov_b32 s50, 0x1c000
	v_mov_b32_e32 v185, v1
	v_add_u32_e32 v208, 0, v5
	v_add_u32_e32 v209, 0, v7
	v_add_u32_e32 v210, 0, v11
	v_add_u32_e32 v211, 0, v13
	v_add_u32_e32 v212, 0, v15
	v_add_u32_e32 v213, 0, v18
	v_add_u32_e32 v214, 0, v19
	v_add_u32_e32 v215, 0, v20
	v_add_u32_e32 v216, 0, v21
	v_add_u32_e32 v217, 0, v22
	v_add_u32_e32 v218, 0, v23
	v_add_u32_e32 v219, 0, v9
	v_mov_b32_e32 v220, 0xf149f2ca
	s_mov_b32 s74, 0
	s_mov_b32 s51, s2
	s_branch .LBB0_238
; DI unsigned short f2bf(float f) { return (unsigned short)(cvtpk(f, f) & 0xffffu); }
; DI int crow(int r, int hi) { return (r & 3) + 8 * (r >> 2) + 4 * hi; }
; DI void attn_item(const bf16_t* __restrict__ Qw_, const bf16_t* __restrict__ Kh, const bf16_t* __restrict__ Vh, const bf16_t* Gw, bf16_t* Ow,
;                   int NT, int kt0, int qw, float sinkv, char* lds) {
;     ...
;     if (hi == 0) li_l[r32] = l_reg; asm volatile("s_waitcnt lgkmcnt(0)" ::: "memory");
;     bf16_t* OT = (bf16_t*)(lds + 67584 + wid * 8704);
; #pragma unroll
;     for (int r = 0; r < 16; ++r) { const int orow = crow(r, hi); const float rl = __builtin_amdgcn_rcpf(li_l[orow]);
; #pragma unroll
;         for (int d0 = 0; d0 < 4; ++d0) OT[orow * 136 + d0 * 32 + r32] = f2bf(o[d0][r] * rl); }
.LBB0_237:
	s_or_b64 exec, exec, s[4:5]
	s_waitcnt lgkmcnt(0)
	v_lshl_add_u32 v0, v193, 2, s54
	s_lshl_b64 s[4:5], s[14:15], 12
	ds_read_b32 v67, v0
	s_add_u32 s4, s23, s4
	s_addc_u32 s5, s30, s5
	s_lshl_b32 s14, s53, 1
	s_add_u32 s4, s4, s14
	s_addc_u32 s5, s5, 0
	s_lshr_b32 s14, s52, 6
	s_mulk_i32 s14, 0x2200
	s_waitcnt lgkmcnt(0)
	v_rcp_f32_e32 v67, v67
	s_add_i32 s14, s14, 0
	s_add_i32 s14, s14, 0x10800
	v_lshl_add_u32 v68, v188, 1, s14
	v_add_u32_e32 v69, v68, v196
	v_mul_f32_e32 v50, v50, v67
	v_mul_f32_e32 v34, v34, v67
	v_mul_f32_e32 v18, v18, v67
	v_cvt_pk_bf16_f32 v50, v50, v50
	ds_write_b16 v69, v50
	v_cvt_pk_bf16_f32 v34, v34, v34
	ds_write_b16 v69, v34 offset:64
	v_cvt_pk_bf16_f32 v18, v18, v18
	v_mul_f32_e32 v2, v2, v67
	ds_write_b16 v69, v18 offset:128
	v_cvt_pk_bf16_f32 v2, v2, v2
	ds_read_b32 v18, v0 offset:4
	ds_write_b16 v69, v2 offset:192
	v_add_u32_e32 v2, v68, v197
	s_waitcnt lgkmcnt(1)
	v_rcp_f32_e32 v18, v18
	s_nop 0
	v_mul_f32_e32 v34, v51, v18
	v_cvt_pk_bf16_f32 v34, v34, v34
	ds_write_b16 v2, v34
	v_mul_f32_e32 v34, v35, v18
	v_mul_f32_e32 v19, v19, v18
	v_mul_f32_e32 v3, v3, v18
	v_cvt_pk_bf16_f32 v34, v34, v34
	ds_write_b16 v2, v34 offset:64
	v_cvt_pk_bf16_f32 v19, v19, v19
	ds_write_b16 v2, v19 offset:128
	v_cvt_pk_bf16_f32 v3, v3, v3
	ds_read_b32 v18, v0 offset:8
	ds_write_b16 v2, v3 offset:192
	s_waitcnt lgkmcnt(1)
	v_rcp_f32_e32 v18, v18
	s_nop 0
	v_mul_f32_e32 v3, v52, v18
	v_cvt_pk_bf16_f32 v3, v3, v3
	ds_write_b16 v2, v3 offset:272
	v_mul_f32_e32 v3, v36, v18
	v_cvt_pk_bf16_f32 v3, v3, v3
	ds_write_b16 v2, v3 offset:336
	v_mul_f32_e32 v3, v20, v18
	v_cvt_pk_bf16_f32 v3, v3, v3
	ds_write_b16 v2, v3 offset:400
	v_mul_f32_e32 v3, v4, v18
	v_cvt_pk_bf16_f32 v3, v3, v3
	ds_read_b32 v4, v0 offset:12
	ds_write_b16 v2, v3 offset:464
	s_waitcnt lgkmcnt(1)
	v_rcp_f32_e32 v4, v4
	s_nop 0
	v_mul_f32_e32 v3, v53, v4
	v_cvt_pk_bf16_f32 v3, v3, v3
	ds_write_b16 v2, v3 offset:544
	v_mul_f32_e32 v3, v37, v4
	v_cvt_pk_bf16_f32 v3, v3, v3
	ds_write_b16 v2, v3 offset:608
	v_mul_f32_e32 v3, v21, v4
	v_cvt_pk_bf16_f32 v3, v3, v3
	ds_write_b16 v2, v3 offset:672
	v_mul_f32_e32 v3, v5, v4
	v_cvt_pk_bf16_f32 v3, v3, v3
	ds_read_b32 v4, v0 offset:32
	ds_write_b16 v2, v3 offset:736
	s_waitcnt lgkmcnt(1)
	v_rcp_f32_e32 v4, v4
	s_nop 0
	v_mul_f32_e32 v3, v54, v4
	v_cvt_pk_bf16_f32 v3, v3, v3
	ds_write_b16 v2, v3 offset:1904
	v_mul_f32_e32 v3, v38, v4
	v_cvt_pk_bf16_f32 v3, v3, v3
	ds_write_b16 v2, v3 offset:1968
	v_mul_f32_e32 v3, v22, v4
	v_cvt_pk_bf16_f32 v3, v3, v3
	ds_write_b16 v2, v3 offset:2032
	v_mul_f32_e32 v3, v6, v4
	v_cvt_pk_bf16_f32 v3, v3, v3
	ds_read_b32 v4, v0 offset:36
	ds_write_b16 v2, v3 offset:2096
	s_waitcnt lgkmcnt(1)
	v_rcp_f32_e32 v4, v4
	s_nop 0
	v_mul_f32_e32 v3, v55, v4
	v_cvt_pk_bf16_f32 v3, v3, v3
	ds_write_b16 v2, v3 offset:2176
	v_mul_f32_e32 v3, v39, v4
	v_cvt_pk_bf16_f32 v3, v3, v3
	ds_write_b16 v2, v3 offset:2240
	v_mul_f32_e32 v3, v23, v4
	v_cvt_pk_bf16_f32 v3, v3, v3
	ds_write_b16 v2, v3 offset:2304
	v_mul_f32_e32 v3, v7, v4
	v_cvt_pk_bf16_f32 v3, v3, v3
	ds_read_b32 v4, v0 offset:40
	ds_write_b16 v2, v3 offset:2368
	v_add_u32_e32 v3, v68, v198
	s_waitcnt lgkmcnt(1)
	v_rcp_f32_e32 v4, v4
	s_nop 0
	v_mul_f32_e32 v5, v56, v4
	v_cvt_pk_bf16_f32 v5, v5, v5
	ds_write_b16 v2, v5 offset:2448
	v_mul_f32_e32 v2, v40, v4
	v_cvt_pk_bf16_f32 v2, v2, v2
	ds_write_b16 v3, v2 offset:64
	v_mul_f32_e32 v2, v24, v4
	v_cvt_pk_bf16_f32 v2, v2, v2
	ds_write_b16 v3, v2 offset:128
	v_mul_f32_e32 v2, v8, v4
	v_cvt_pk_bf16_f32 v2, v2, v2
	ds_read_b32 v4, v0 offset:44
	ds_write_b16 v3, v2 offset:192
	s_waitcnt lgkmcnt(1)
	v_rcp_f32_e32 v4, v4
	s_nop 0
	v_mul_f32_e32 v2, v57, v4
	v_cvt_pk_bf16_f32 v2, v2, v2
	ds_write_b16 v3, v2 offset:272
	v_mul_f32_e32 v2, v41, v4
	v_cvt_pk_bf16_f32 v2, v2, v2
	ds_write_b16 v3, v2 offset:336
	v_mul_f32_e32 v2, v25, v4
	v_cvt_pk_bf16_f32 v2, v2, v2
	ds_write_b16 v3, v2 offset:400
	v_mul_f32_e32 v2, v9, v4
	v_cvt_pk_bf16_f32 v2, v2, v2
	ds_read_b32 v4, v0 offset:64
	ds_write_b16 v3, v2 offset:464
	s_waitcnt lgkmcnt(1)
	v_rcp_f32_e32 v4, v4
	s_nop 0
	v_mul_f32_e32 v2, v58, v4
	v_cvt_pk_bf16_f32 v2, v2, v2
	ds_write_b16 v3, v2 offset:1632
	v_mul_f32_e32 v2, v42, v4
	v_cvt_pk_bf16_f32 v2, v2, v2
	ds_write_b16 v3, v2 offset:1696
	v_mul_f32_e32 v2, v26, v4
	v_cvt_pk_bf16_f32 v2, v2, v2
	ds_write_b16 v3, v2 offset:1760
	v_mul_f32_e32 v2, v10, v4
	v_cvt_pk_bf16_f32 v2, v2, v2
	ds_read_b32 v4, v0 offset:68
	ds_write_b16 v3, v2 offset:1824
	s_waitcnt lgkmcnt(1)
	v_rcp_f32_e32 v4, v4
	s_nop 0
	v_mul_f32_e32 v2, v59, v4
	v_cvt_pk_bf16_f32 v2, v2, v2
	ds_write_b16 v3, v2 offset:1904
	v_mul_f32_e32 v2, v43, v4
	v_cvt_pk_bf16_f32 v2, v2, v2
	ds_write_b16 v3, v2 offset:1968
	v_mul_f32_e32 v2, v27, v4
	v_cvt_pk_bf16_f32 v2, v2, v2
	ds_write_b16 v3, v2 offset:2032
	v_mul_f32_e32 v2, v11, v4
	v_cvt_pk_bf16_f32 v2, v2, v2
	ds_read_b32 v4, v0 offset:72
	ds_write_b16 v3, v2 offset:2096
	s_waitcnt lgkmcnt(1)
	v_rcp_f32_e32 v4, v4
	s_nop 0
	v_mul_f32_e32 v2, v60, v4
	v_cvt_pk_bf16_f32 v2, v2, v2
	ds_write_b16 v3, v2 offset:2176
	v_mul_f32_e32 v2, v44, v4
	v_cvt_pk_bf16_f32 v2, v2, v2
	ds_write_b16 v3, v2 offset:2240
	v_mul_f32_e32 v2, v28, v4
	v_cvt_pk_bf16_f32 v2, v2, v2
	ds_write_b16 v3, v2 offset:2304
	v_mul_f32_e32 v2, v12, v4
	v_cvt_pk_bf16_f32 v2, v2, v2
	ds_read_b32 v4, v0 offset:76
	ds_write_b16 v3, v2 offset:2368
	s_waitcnt lgkmcnt(1)
	v_rcp_f32_e32 v4, v4
	s_nop 0
	v_mul_f32_e32 v2, v61, v4
	v_cvt_pk_bf16_f32 v2, v2, v2
	ds_write_b16 v3, v2 offset:2448
	v_mul_f32_e32 v2, v45, v4
	v_cvt_pk_bf16_f32 v2, v2, v2
	ds_write_b16 v3, v2 offset:2512
	v_mul_f32_e32 v2, v29, v4
	v_cvt_pk_bf16_f32 v2, v2, v2
	ds_write_b16 v3, v2 offset:2576
	v_mul_f32_e32 v2, v13, v4
	v_cvt_pk_bf16_f32 v2, v2, v2
	ds_read_b32 v4, v0 offset:96
	ds_write_b16 v3, v2 offset:2640
	s_waitcnt lgkmcnt(1)
; DI unsigned cvtpk(float lo, float hi) { unsigned r; asm volatile("v_cvt_pk_bf16_f32 %0, %1, %2" : "=v"(r) : "v"(lo), "v"(hi)); return r; }
; DI float bflo(unsigned w) { return __uint_as_float(w << 16); }
; DI float bfhi(unsigned w) { return __uint_as_float(w & 0xffff0000u); }
; DI unsigned short f2bf(float f) { return (unsigned short)(cvtpk(f, f) & 0xffffu); }
; DI float sigm(float x) { return rcpf_(1.f + ex2(-x * LOG2E)); }
; DI int crow(int r, int hi) { return (r & 3) + 8 * (r >> 2) + 4 * hi; }
; DI void attn_item(const bf16_t* __restrict__ Qw_, const bf16_t* __restrict__ Kh, const bf16_t* __restrict__ Vh, const bf16_t* Gw, bf16_t* Ow,
;                   int NT, int kt0, int qw, float sinkv, char* lds) {
;     ...
;     for (int r = 0; r < 16; ++r) { const int orow = crow(r, hi); const float rl = __builtin_amdgcn_rcpf(li_l[orow]);
; #pragma unroll
;         for (int d0 = 0; d0 < 4; ++d0) OT[orow * 136 + d0 * 32 + r32] = f2bf(o[d0][r] * rl); }
;     __builtin_amdgcn_sched_barrier(0);
;     u32x4 gv[8];
; #pragma unroll
;     for (int k = 0; k < 8; ++k) gv[k] = __builtin_nontemporal_load((const u32x4*)(Gw + (size_t)(er + 4 * k) * 2048 + ec * 8));
;     asm volatile("s_waitcnt lgkmcnt(0)" ::: "memory");
; #pragma unroll
;     for (int k = 0; k < 8; ++k) {
;         const u32x4 ov = *(const u32x4*)(OT + (er + 4 * k) * 136 + ec * 8); u32x4 w;
; #pragma unroll
;         for (int i = 0; i < 4; ++i) { const float g0 = bflo(gv[k][i]), g1 = bfhi(gv[k][i]); w[i] = cvtpk(bflo(ov[i]) * g0 * sigm(g0), bfhi(ov[i]) * g1 * sigm(g1)); }
; DI void phase_att(const Params& p, unsigned char* shm) {
;     ...
;     for (int it = blockIdx.x; it < 1024; it += gridDim.x) {
;         const int hp = it & 1, g = (it >> 1) & 3, n = it >> 3;
;         const int head = g * 4 + hp * 2 + (wid >> 2), qw = 32 * (wid & 3);
;         const int kfirst = n == 0 ? 0 : (n - 1) * 128, NT = (n == 0 || n == 127) ? 4 : 6, kt0 = kfirst - n * 128;
;         __syncthreads();
;         const size_t go = (size_t)(n * 128 + qw) * 2048 + head * 128;
;         att::attn_item(Z + (size_t)(n * 128 + qw) * 3072 + head * 128, Z + (size_t)kfirst * 3072 + 2048 + g * 128, Z + (size_t)kfirst * 3072 + 2560 + g * 128,
;                        GA + go, YB + go, NT, kt0, qw, p.in[10][head], (char*)shm);
	v_rcp_f32_e32 v4, v4
	s_nop 0
	v_mul_f32_e32 v2, v62, v4
	v_cvt_pk_bf16_f32 v2, v2, v2
	ds_write_b16 v3, v2 offset:3808
	v_mul_f32_e32 v2, v46, v4
	v_cvt_pk_bf16_f32 v2, v2, v2
	ds_write_b16 v3, v2 offset:3872
	v_mul_f32_e32 v2, v30, v4
	v_cvt_pk_bf16_f32 v2, v2, v2
	ds_write_b16 v3, v2 offset:3936
	v_mul_f32_e32 v2, v14, v4
	v_cvt_pk_bf16_f32 v2, v2, v2
	ds_read_b32 v4, v0 offset:100
	ds_write_b16 v3, v2 offset:4000
	s_waitcnt lgkmcnt(1)
	v_rcp_f32_e32 v4, v4
	s_nop 0
	v_mul_f32_e32 v2, v63, v4
	v_cvt_pk_bf16_f32 v2, v2, v2
	ds_write_b16 v3, v2 offset:4080
	v_mul_f32_e32 v2, v47, v4
	v_cvt_pk_bf16_f32 v2, v2, v2
	ds_write_b16 v3, v2 offset:4144
	v_mul_f32_e32 v2, v31, v4
	v_cvt_pk_bf16_f32 v2, v2, v2
	ds_write_b16 v3, v2 offset:4208
	v_mul_f32_e32 v2, v15, v4
	v_cvt_pk_bf16_f32 v2, v2, v2
	ds_read_b32 v4, v0 offset:104
	ds_write_b16 v3, v2 offset:4272
	s_waitcnt lgkmcnt(1)
	v_rcp_f32_e32 v4, v4
	s_nop 0
	v_mul_f32_e32 v2, v64, v4
	v_cvt_pk_bf16_f32 v2, v2, v2
	ds_write_b16 v3, v2 offset:4352
	v_mul_f32_e32 v2, v48, v4
	v_cvt_pk_bf16_f32 v2, v2, v2
	ds_write_b16 v3, v2 offset:4416
	v_mul_f32_e32 v2, v32, v4
	v_cvt_pk_bf16_f32 v2, v2, v2
	ds_write_b16 v3, v2 offset:4480
	v_mul_f32_e32 v2, v16, v4
	v_cvt_pk_bf16_f32 v4, v2, v2
	ds_read_b32 v0, v0 offset:108
	ds_write_b16 v3, v4 offset:4544
	v_ashrrev_i32_e32 v2, 4, v66
	s_waitcnt lgkmcnt(1)
	v_rcp_f32_e32 v0, v0
	s_nop 0
	v_mul_f32_e32 v4, v65, v0
	v_cvt_pk_bf16_f32 v4, v4, v4
	ds_write_b16 v3, v4 offset:4624
	v_mul_f32_e32 v4, v49, v0
	v_cvt_pk_bf16_f32 v4, v4, v4
	ds_write_b16 v3, v4 offset:4688
	v_mul_f32_e32 v4, v33, v0
	v_mul_f32_e32 v0, v17, v0
	v_cvt_pk_bf16_f32 v4, v4, v4
	ds_write_b16 v3, v4 offset:4752
	v_cvt_pk_bf16_f32 v0, v0, v0
	ds_write_b16 v3, v0 offset:4816
	v_lshlrev_b32_e32 v0, 4, v66
	v_and_b32_e32 v0, 0xf0, v0
	v_ashrrev_i32_e32 v3, 31, v2
	v_lshl_add_u64 v[4:5], s[4:5], 0, v[0:1]
	v_lshlrev_b64 v[6:7], 12, v[2:3]
	v_lshl_add_u64 v[50:51], v[4:5], 0, v[6:7]
	global_load_dwordx4 v[38:41], v[50:51], off nt
	v_add_co_u32_e32 v52, vcc, s38, v50
	v_mul_lo_u32 v2, v2, s39
	s_nop 0
	v_addc_co_u32_e32 v53, vcc, 0, v51, vcc
	v_add_co_u32_e32 v36, vcc, s47, v50
	v_add3_u32 v0, s14, v0, v2
	s_nop 0
	v_addc_co_u32_e32 v37, vcc, 0, v51, vcc
	v_add_co_u32_e32 v34, vcc, s48, v50
	s_add_i32 s51, s51, s24
	s_nop 0
	v_addc_co_u32_e32 v35, vcc, 0, v51, vcc
	v_add_co_u32_e32 v32, vcc, s42, v50
	s_cmpk_lt_i32 s51, 0x400
	s_nop 0
	v_addc_co_u32_e32 v33, vcc, 0, v51, vcc
	v_add_co_u32_e32 v30, vcc, s49, v50
	s_waitcnt vmcnt(0)
	v_lshlrev_b32_e32 v57, 16, v38
	v_addc_co_u32_e32 v31, vcc, 0, v51, vcc
	v_add_co_u32_e32 v28, vcc, s36, v50
	v_and_b32_e32 v38, 0xffff0000, v38
	s_nop 0
	v_addc_co_u32_e32 v29, vcc, 0, v51, vcc
	v_add_co_u32_e32 v26, vcc, s50, v50
	v_lshlrev_b32_e32 v58, 16, v39
	s_nop 0
	v_addc_co_u32_e32 v27, vcc, 0, v51, vcc
	global_load_dwordx4 v[42:45], v[52:53], off nt
	global_load_dwordx4 v[22:25], v[36:37], off nt
	global_load_dwordx4 v[18:21], v[34:35], off nt
	global_load_dwordx4 v[14:17], v[32:33], off nt
	global_load_dwordx4 v[10:13], v[30:31], off nt
	global_load_dwordx4 v[6:9], v[28:29], off nt
	global_load_dwordx4 v[2:5], v[26:27], off nt
	s_cselect_b32 s60, 0, s24
	s_sub_i32 s60, s51, s60
	s_lshl_b32 s61, s60, 1
	s_and_b32 s61, s61, 2
	s_bfe_u32 s62, s60, 0x20001
	s_lshl_b32 s63, s62, 2
	s_add_i32 s61, s61, s31
	s_add_i32 s61, s61, s63
	s_lshl_b32 s75, s61, 2
	s_ashr_i32 s63, s60, 3
	s_lshl_b32 s63, s63, 7
	s_or_b32 s64, s63, s34
	s_mul_i32 s65, s64, 0x1800
	s_mul_hi_i32 s66, s64, 0x1800
	s_add_u32 s65, s11, s65
	s_addc_u32 s66, s22, s66
	s_lshl_b32 s61, s61, 8
	s_add_u32 s68, s65, s61
	s_addc_u32 s69, s66, 0
	s_add_i32 s63, s63, 0xffffff80
	s_mul_i32 s65, s63, 0x1800
	s_mul_hi_i32 s66, s63, 0x1800
	s_add_u32 s65, s11, s65
	s_addc_u32 s66, s22, s66
	s_lshl_b32 s62, s62, 8
	s_add_u32 s65, s65, s62
	s_addc_u32 s66, s66, 0
	s_add_u32 s76, s65, 0x1000
	s_addc_u32 s77, s66, 0
	s_add_u32 s78, s65, 0x1400
	s_addc_u32 s79, s66, 0
	global_load_dwordx4 v[130:133], v200, s[78:79]
	global_load_dwordx4 v[134:137], v201, s[78:79]
	global_load_dwordx4 v[138:141], v200, s[76:77]
	global_load_dwordx4 v[142:145], v201, s[76:77]
	v_lshl_add_u64 v[60:61], s[68:69], 0, v[178:179]
	v_lshl_add_u64 v[60:61], v[60:61], 0, v[184:185]
	global_load_dwordx4 v[126:129], v[60:61], off
	global_load_dwordx4 v[122:125], v[60:61], off offset:32
	global_load_dwordx4 v[118:121], v[60:61], off offset:64
	global_load_dwordx4 v[114:117], v[60:61], off offset:96
	global_load_dwordx4 v[110:113], v[60:61], off offset:128
	global_load_dwordx4 v[106:109], v[60:61], off offset:160
	global_load_dwordx4 v[102:105], v[60:61], off offset:192
	global_load_dwordx4 v[98:101], v[60:61], off offset:224
	v_mov_b32_e32 v62, s75
	global_load_dword v62, v62, s[8:9]
	s_mov_b32 s74, 1
	s_cmpk_lt_i32 s51, 0x400
	s_waitcnt lgkmcnt(0)
	ds_read_b128 v[46:49], v0
	v_and_b32_e32 v39, 0xffff0000, v39
	v_lshlrev_b32_e32 v59, 16, v40
	v_and_b32_e32 v40, 0xffff0000, v40
	s_waitcnt lgkmcnt(0)
; DI unsigned cvtpk(float lo, float hi) { unsigned r; asm volatile("v_cvt_pk_bf16_f32 %0, %1, %2" : "=v"(r) : "v"(lo), "v"(hi)); return r; }
; DI float bflo(unsigned w) { return __uint_as_float(w << 16); }
; DI float bfhi(unsigned w) { return __uint_as_float(w & 0xffff0000u); }
; DI float sigm(float x) { return rcpf_(1.f + ex2(-x * LOG2E)); }
; DI void attn_item(const bf16_t* __restrict__ Qw_, const bf16_t* __restrict__ Kh, const bf16_t* __restrict__ Vh, const bf16_t* Gw, bf16_t* Ow,
;                   int NT, int kt0, int qw, float sinkv, char* lds) {
;     ...
; #pragma unroll
;     for (int k = 0; k < 8; ++k) {
;         const u32x4 ov = *(const u32x4*)(OT + (er + 4 * k) * 136 + ec * 8); u32x4 w;
; #pragma unroll
;         for (int i = 0; i < 4; ++i) { const float g0 = bflo(gv[k][i]), g1 = bfhi(gv[k][i]); w[i] = cvtpk(bflo(ov[i]) * g0 * sigm(g0), bfhi(ov[i]) * g1 * sigm(g1)); }
;         __builtin_nontemporal_store(w, (u32x4*)(Ow + (size_t)(er + 4 * k) * 2048 + ec * 8));
;     }
	v_lshlrev_b32_e32 v54, 16, v46
	v_and_b32_e32 v46, 0xffff0000, v46
	v_lshlrev_b32_e32 v55, 16, v47
	v_and_b32_e32 v47, 0xffff0000, v47
	v_mul_f32_e32 v46, v46, v38
	v_mul_f32_e32 v38, 0xbfb8aa3b, v38
	v_mul_f32_e32 v55, v55, v58
	v_mul_f32_e32 v58, 0xbfb8aa3b, v58
	v_mul_f32_e32 v47, v47, v39
	v_mul_f32_e32 v39, 0xbfb8aa3b, v39
	v_lshlrev_b32_e32 v56, 16, v48
	v_and_b32_e32 v48, 0xffff0000, v48
	v_mul_f32_e32 v54, v54, v57
	v_mul_f32_e32 v57, 0xbfb8aa3b, v57
	v_exp_f32_e32 v38, v38
	v_exp_f32_e32 v58, v58
	v_exp_f32_e32 v39, v39
	v_mul_f32_e32 v48, v48, v40
	v_mul_f32_e32 v40, 0xbfb8aa3b, v40
	v_exp_f32_e32 v57, v57
	v_exp_f32_e32 v40, v40
	v_add_f32_e32 v38, 1.0, v38
	v_add_f32_e32 v58, 1.0, v58
	v_add_f32_e32 v39, 1.0, v39
	v_add_f32_e32 v57, 1.0, v57
	v_rcp_f32_e32 v38, v38
	v_rcp_f32_e32 v58, v58
	v_rcp_f32_e32 v39, v39
	v_mul_f32_e32 v56, v56, v59
	v_mul_f32_e32 v59, 0xbfb8aa3b, v59
	v_add_f32_e32 v40, 1.0, v40
	v_rcp_f32_e32 v57, v57
	v_exp_f32_e32 v59, v59
	v_rcp_f32_e32 v40, v40
	v_mul_f32_e32 v38, v38, v46
	v_mul_f32_e32 v46, v58, v55
	v_mul_f32_e32 v39, v39, v47
	v_mul_f32_e32 v54, v57, v54
	v_cvt_pk_bf16_f32 v38, v54, v38
	v_cvt_pk_bf16_f32 v39, v46, v39
	v_lshlrev_b32_e32 v46, 16, v41
	v_add_f32_e32 v59, 1.0, v59
	v_mul_f32_e32 v40, v40, v48
	v_mul_f32_e32 v48, 0xbfb8aa3b, v46
	v_rcp_f32_e32 v59, v59
	v_exp_f32_e32 v48, v48
	v_and_b32_e32 v41, 0xffff0000, v41
	v_mul_f32_e32 v54, 0xbfb8aa3b, v41
	v_exp_f32_e32 v54, v54
	v_mul_f32_e32 v47, v59, v56
	v_add_f32_e32 v48, 1.0, v48
	v_cvt_pk_bf16_f32 v40, v47, v40
	v_lshlrev_b32_e32 v47, 16, v49
	v_rcp_f32_e32 v48, v48
	v_mul_f32_e32 v46, v47, v46
	v_add_f32_e32 v47, 1.0, v54
	v_rcp_f32_e32 v47, v47
	v_mul_f32_e32 v46, v48, v46
	v_and_b32_e32 v48, 0xffff0000, v49
	v_mul_f32_e32 v41, v48, v41
	v_mul_f32_e32 v41, v47, v41
	v_cvt_pk_bf16_f32 v41, v46, v41
	global_store_dwordx4 v[50:51], v[38:41], off nt
	ds_read_b128 v[46:49], v0 offset:1088
	s_waitcnt vmcnt(20)
	v_lshlrev_b32_e32 v38, 16, v42
	v_mul_f32_e32 v40, 0xbfb8aa3b, v38
	v_exp_f32_e32 v40, v40
	v_and_b32_e32 v41, 0xffff0000, v42
	v_mul_f32_e32 v42, 0xbfb8aa3b, v41
	v_exp_f32_e32 v42, v42
	v_add_f32_e32 v40, 1.0, v40
	s_waitcnt lgkmcnt(0)
	v_lshlrev_b32_e32 v39, 16, v46
	v_rcp_f32_e32 v40, v40
	v_mul_f32_e32 v38, v39, v38
	v_add_f32_e32 v39, 1.0, v42
	v_rcp_f32_e32 v39, v39
	v_mul_f32_e32 v38, v40, v38
	v_and_b32_e32 v40, 0xffff0000, v46
	v_mul_f32_e32 v40, v40, v41
	v_mul_f32_e32 v39, v39, v40
	v_cvt_pk_bf16_f32 v38, v38, v39
	v_lshlrev_b32_e32 v39, 16, v43
	v_mul_f32_e32 v41, 0xbfb8aa3b, v39
	v_exp_f32_e32 v41, v41
	v_and_b32_e32 v42, 0xffff0000, v43
	v_mul_f32_e32 v43, 0xbfb8aa3b, v42
	v_exp_f32_e32 v43, v43
	v_add_f32_e32 v41, 1.0, v41
	v_lshlrev_b32_e32 v40, 16, v47
	v_rcp_f32_e32 v41, v41
	v_mul_f32_e32 v39, v40, v39
	v_add_f32_e32 v40, 1.0, v43
	v_rcp_f32_e32 v40, v40
	v_mul_f32_e32 v39, v41, v39
	v_and_b32_e32 v41, 0xffff0000, v47
	v_mul_f32_e32 v41, v41, v42
	v_mul_f32_e32 v40, v40, v41
	v_cvt_pk_bf16_f32 v39, v39, v40
	v_lshlrev_b32_e32 v40, 16, v44
	v_mul_f32_e32 v42, 0xbfb8aa3b, v40
	v_exp_f32_e32 v42, v42
	v_and_b32_e32 v43, 0xffff0000, v44
	v_mul_f32_e32 v44, 0xbfb8aa3b, v43
	v_exp_f32_e32 v44, v44
	v_add_f32_e32 v42, 1.0, v42
	v_lshlrev_b32_e32 v41, 16, v48
	v_rcp_f32_e32 v42, v42
	v_mul_f32_e32 v40, v41, v40
	v_add_f32_e32 v41, 1.0, v44
	v_rcp_f32_e32 v41, v41
	v_mul_f32_e32 v40, v42, v40
	v_and_b32_e32 v42, 0xffff0000, v48
	v_mul_f32_e32 v42, v42, v43
	v_mul_f32_e32 v41, v41, v42
	v_cvt_pk_bf16_f32 v40, v40, v41
	v_lshlrev_b32_e32 v41, 16, v45
	v_mul_f32_e32 v43, 0xbfb8aa3b, v41
	v_exp_f32_e32 v43, v43
	v_and_b32_e32 v44, 0xffff0000, v45
	v_mul_f32_e32 v45, 0xbfb8aa3b, v44
	v_exp_f32_e32 v45, v45
	v_add_f32_e32 v43, 1.0, v43
	v_lshlrev_b32_e32 v42, 16, v49
	v_rcp_f32_e32 v43, v43
	v_mul_f32_e32 v41, v42, v41
	v_add_f32_e32 v42, 1.0, v45
	v_rcp_f32_e32 v42, v42
	v_mul_f32_e32 v41, v43, v41
	v_and_b32_e32 v43, 0xffff0000, v49
	v_mul_f32_e32 v43, v43, v44
	v_mul_f32_e32 v42, v42, v43
	v_cvt_pk_bf16_f32 v41, v41, v42
	global_store_dwordx4 v[52:53], v[38:41], off nt
	ds_read_b128 v[42:45], v0 offset:2176
	s_waitcnt vmcnt(20)
	v_lshlrev_b32_e32 v38, 16, v22
	v_mul_f32_e32 v40, 0xbfb8aa3b, v38
	v_exp_f32_e32 v40, v40
	v_and_b32_e32 v22, 0xffff0000, v22
	v_mul_f32_e32 v41, 0xbfb8aa3b, v22
	v_exp_f32_e32 v41, v41
	v_add_f32_e32 v40, 1.0, v40
	s_waitcnt lgkmcnt(0)
	v_lshlrev_b32_e32 v39, 16, v42
	v_rcp_f32_e32 v40, v40
	v_mul_f32_e32 v38, v39, v38
	v_add_f32_e32 v39, 1.0, v41
	v_rcp_f32_e32 v39, v39
	v_mul_f32_e32 v38, v40, v38
	v_and_b32_e32 v40, 0xffff0000, v42
	v_mul_f32_e32 v22, v40, v22
	v_mul_f32_e32 v22, v39, v22
	v_cvt_pk_bf16_f32 v22, v38, v22
	v_lshlrev_b32_e32 v38, 16, v23
	v_mul_f32_e32 v40, 0xbfb8aa3b, v38
	v_exp_f32_e32 v40, v40
	v_and_b32_e32 v23, 0xffff0000, v23
	v_mul_f32_e32 v41, 0xbfb8aa3b, v23
	v_exp_f32_e32 v41, v41
	v_add_f32_e32 v40, 1.0, v40
	v_lshlrev_b32_e32 v39, 16, v43
	v_rcp_f32_e32 v40, v40
	v_mul_f32_e32 v38, v39, v38
	v_add_f32_e32 v39, 1.0, v41
	v_rcp_f32_e32 v39, v39
	v_mul_f32_e32 v38, v40, v38
	v_and_b32_e32 v40, 0xffff0000, v43
	v_mul_f32_e32 v23, v40, v23
	v_mul_f32_e32 v23, v39, v23
	v_cvt_pk_bf16_f32 v23, v38, v23
	v_lshlrev_b32_e32 v38, 16, v24
	v_mul_f32_e32 v40, 0xbfb8aa3b, v38
	v_exp_f32_e32 v40, v40
	v_and_b32_e32 v24, 0xffff0000, v24
	v_mul_f32_e32 v41, 0xbfb8aa3b, v24
	v_exp_f32_e32 v41, v41
	v_add_f32_e32 v40, 1.0, v40
	v_lshlrev_b32_e32 v39, 16, v44
	v_rcp_f32_e32 v40, v40
	v_mul_f32_e32 v38, v39, v38
	v_add_f32_e32 v39, 1.0, v41
	v_rcp_f32_e32 v39, v39
	v_mul_f32_e32 v38, v40, v38
	v_and_b32_e32 v40, 0xffff0000, v44
	v_mul_f32_e32 v24, v40, v24
	v_mul_f32_e32 v24, v39, v24
	v_cvt_pk_bf16_f32 v24, v38, v24
	v_lshlrev_b32_e32 v38, 16, v25
	v_mul_f32_e32 v40, 0xbfb8aa3b, v38
	v_exp_f32_e32 v40, v40
	v_and_b32_e32 v25, 0xffff0000, v25
	v_mul_f32_e32 v41, 0xbfb8aa3b, v25
	v_exp_f32_e32 v41, v41
	v_add_f32_e32 v40, 1.0, v40
	v_lshlrev_b32_e32 v39, 16, v45
	v_rcp_f32_e32 v40, v40
	v_mul_f32_e32 v38, v39, v38
	v_add_f32_e32 v39, 1.0, v41
	v_rcp_f32_e32 v39, v39
	v_mul_f32_e32 v38, v40, v38
	v_and_b32_e32 v40, 0xffff0000, v45
	v_mul_f32_e32 v25, v40, v25
	v_mul_f32_e32 v25, v39, v25
	v_cvt_pk_bf16_f32 v25, v38, v25
	global_store_dwordx4 v[36:37], v[22:25], off nt
	ds_read_b128 v[38:41], v0 offset:3264
	s_waitcnt vmcnt(20)
; DI unsigned cvtpk(float lo, float hi) { unsigned r; asm volatile("v_cvt_pk_bf16_f32 %0, %1, %2" : "=v"(r) : "v"(lo), "v"(hi)); return r; }
; DI float bflo(unsigned w) { return __uint_as_float(w << 16); }
; DI float bfhi(unsigned w) { return __uint_as_float(w & 0xffff0000u); }
; DI float sigm(float x) { return rcpf_(1.f + ex2(-x * LOG2E)); }
; DI void attn_item(const bf16_t* __restrict__ Qw_, const bf16_t* __restrict__ Kh, const bf16_t* __restrict__ Vh, const bf16_t* Gw, bf16_t* Ow,
;                   int NT, int kt0, int qw, float sinkv, char* lds) {
;     ...
; #pragma unroll
;     for (int k = 0; k < 8; ++k) {
;         const u32x4 ov = *(const u32x4*)(OT + (er + 4 * k) * 136 + ec * 8); u32x4 w;
; #pragma unroll
;         for (int i = 0; i < 4; ++i) { const float g0 = bflo(gv[k][i]), g1 = bfhi(gv[k][i]); w[i] = cvtpk(bflo(ov[i]) * g0 * sigm(g0), bfhi(ov[i]) * g1 * sigm(g1)); }
;         __builtin_nontemporal_store(w, (u32x4*)(Ow + (size_t)(er + 4 * k) * 2048 + ec * 8));
;     }
	v_lshlrev_b32_e32 v22, 16, v18
	v_mul_f32_e32 v24, 0xbfb8aa3b, v22
	v_exp_f32_e32 v24, v24
	v_and_b32_e32 v18, 0xffff0000, v18
	v_mul_f32_e32 v25, 0xbfb8aa3b, v18
	v_exp_f32_e32 v25, v25
	v_add_f32_e32 v24, 1.0, v24
	s_waitcnt lgkmcnt(0)
	v_lshlrev_b32_e32 v23, 16, v38
	v_rcp_f32_e32 v24, v24
	v_mul_f32_e32 v22, v23, v22
	v_add_f32_e32 v23, 1.0, v25
	v_rcp_f32_e32 v23, v23
	v_mul_f32_e32 v22, v24, v22
	v_and_b32_e32 v24, 0xffff0000, v38
	v_mul_f32_e32 v18, v24, v18
	v_mul_f32_e32 v18, v23, v18
	v_cvt_pk_bf16_f32 v18, v22, v18
	v_lshlrev_b32_e32 v22, 16, v19
	v_mul_f32_e32 v24, 0xbfb8aa3b, v22
	v_exp_f32_e32 v24, v24
	v_and_b32_e32 v19, 0xffff0000, v19
	v_mul_f32_e32 v25, 0xbfb8aa3b, v19
	v_exp_f32_e32 v25, v25
	v_add_f32_e32 v24, 1.0, v24
	v_lshlrev_b32_e32 v23, 16, v39
	v_rcp_f32_e32 v24, v24
	v_mul_f32_e32 v22, v23, v22
	v_add_f32_e32 v23, 1.0, v25
	v_rcp_f32_e32 v23, v23
	v_mul_f32_e32 v22, v24, v22
	v_and_b32_e32 v24, 0xffff0000, v39
	v_mul_f32_e32 v19, v24, v19
	v_mul_f32_e32 v19, v23, v19
	v_cvt_pk_bf16_f32 v19, v22, v19
	v_lshlrev_b32_e32 v22, 16, v20
	v_mul_f32_e32 v24, 0xbfb8aa3b, v22
	v_exp_f32_e32 v24, v24
	v_and_b32_e32 v20, 0xffff0000, v20
	v_mul_f32_e32 v25, 0xbfb8aa3b, v20
	v_exp_f32_e32 v25, v25
	v_add_f32_e32 v24, 1.0, v24
	v_lshlrev_b32_e32 v23, 16, v40
	v_rcp_f32_e32 v24, v24
	v_mul_f32_e32 v22, v23, v22
	v_add_f32_e32 v23, 1.0, v25
	v_rcp_f32_e32 v23, v23
	v_mul_f32_e32 v22, v24, v22
	v_and_b32_e32 v24, 0xffff0000, v40
	v_mul_f32_e32 v20, v24, v20
	v_mul_f32_e32 v20, v23, v20
	v_cvt_pk_bf16_f32 v20, v22, v20
	v_lshlrev_b32_e32 v22, 16, v21
	v_mul_f32_e32 v24, 0xbfb8aa3b, v22
	v_exp_f32_e32 v24, v24
	v_and_b32_e32 v21, 0xffff0000, v21
	v_mul_f32_e32 v25, 0xbfb8aa3b, v21
	v_exp_f32_e32 v25, v25
	v_add_f32_e32 v24, 1.0, v24
	v_lshlrev_b32_e32 v23, 16, v41
	v_rcp_f32_e32 v24, v24
	v_mul_f32_e32 v22, v23, v22
	v_add_f32_e32 v23, 1.0, v25
	v_rcp_f32_e32 v23, v23
	v_mul_f32_e32 v22, v24, v22
	v_and_b32_e32 v24, 0xffff0000, v41
	v_mul_f32_e32 v21, v24, v21
	v_mul_f32_e32 v21, v23, v21
	v_cvt_pk_bf16_f32 v21, v22, v21
	global_store_dwordx4 v[34:35], v[18:21], off nt
	ds_read_b128 v[22:25], v0 offset:4352
	s_waitcnt vmcnt(20)
	v_lshlrev_b32_e32 v18, 16, v14
	v_mul_f32_e32 v20, 0xbfb8aa3b, v18
	v_exp_f32_e32 v20, v20
	v_and_b32_e32 v14, 0xffff0000, v14
	v_mul_f32_e32 v21, 0xbfb8aa3b, v14
	v_exp_f32_e32 v21, v21
	v_add_f32_e32 v20, 1.0, v20
	s_waitcnt lgkmcnt(0)
	v_lshlrev_b32_e32 v19, 16, v22
	v_rcp_f32_e32 v20, v20
	v_mul_f32_e32 v18, v19, v18
	v_add_f32_e32 v19, 1.0, v21
	v_rcp_f32_e32 v19, v19
	v_mul_f32_e32 v18, v20, v18
	v_and_b32_e32 v20, 0xffff0000, v22
	v_mul_f32_e32 v14, v20, v14
	v_mul_f32_e32 v14, v19, v14
	v_cvt_pk_bf16_f32 v14, v18, v14
	v_lshlrev_b32_e32 v18, 16, v15
	v_mul_f32_e32 v20, 0xbfb8aa3b, v18
	v_exp_f32_e32 v20, v20
	v_and_b32_e32 v15, 0xffff0000, v15
	v_mul_f32_e32 v21, 0xbfb8aa3b, v15
	v_exp_f32_e32 v21, v21
	v_add_f32_e32 v20, 1.0, v20
	v_lshlrev_b32_e32 v19, 16, v23
	v_rcp_f32_e32 v20, v20
	v_mul_f32_e32 v18, v19, v18
	v_add_f32_e32 v19, 1.0, v21
	v_rcp_f32_e32 v19, v19
	v_mul_f32_e32 v18, v20, v18
	v_and_b32_e32 v20, 0xffff0000, v23
	v_mul_f32_e32 v15, v20, v15
	v_mul_f32_e32 v15, v19, v15
	v_cvt_pk_bf16_f32 v15, v18, v15
	v_lshlrev_b32_e32 v18, 16, v16
	v_mul_f32_e32 v20, 0xbfb8aa3b, v18
	v_exp_f32_e32 v20, v20
	v_and_b32_e32 v16, 0xffff0000, v16
	v_mul_f32_e32 v21, 0xbfb8aa3b, v16
	v_exp_f32_e32 v21, v21
	v_add_f32_e32 v20, 1.0, v20
	v_lshlrev_b32_e32 v19, 16, v24
	v_rcp_f32_e32 v20, v20
	v_mul_f32_e32 v18, v19, v18
	v_add_f32_e32 v19, 1.0, v21
	v_rcp_f32_e32 v19, v19
	v_mul_f32_e32 v18, v20, v18
	v_and_b32_e32 v20, 0xffff0000, v24
	v_mul_f32_e32 v16, v20, v16
	v_mul_f32_e32 v16, v19, v16
	v_cvt_pk_bf16_f32 v16, v18, v16
	v_lshlrev_b32_e32 v18, 16, v17
	v_mul_f32_e32 v20, 0xbfb8aa3b, v18
	v_exp_f32_e32 v20, v20
	v_and_b32_e32 v17, 0xffff0000, v17
	v_mul_f32_e32 v21, 0xbfb8aa3b, v17
	v_exp_f32_e32 v21, v21
	v_add_f32_e32 v20, 1.0, v20
	v_lshlrev_b32_e32 v19, 16, v25
	v_rcp_f32_e32 v20, v20
	v_mul_f32_e32 v18, v19, v18
	v_add_f32_e32 v19, 1.0, v21
	v_rcp_f32_e32 v19, v19
	v_mul_f32_e32 v18, v20, v18
	v_and_b32_e32 v20, 0xffff0000, v25
	v_mul_f32_e32 v17, v20, v17
	v_mul_f32_e32 v17, v19, v17
	v_cvt_pk_bf16_f32 v17, v18, v17
	global_store_dwordx4 v[32:33], v[14:17], off nt
	ds_read_b128 v[18:21], v0 offset:5440
	s_waitcnt vmcnt(20)
	v_lshlrev_b32_e32 v14, 16, v10
	v_mul_f32_e32 v16, 0xbfb8aa3b, v14
	v_exp_f32_e32 v16, v16
	v_and_b32_e32 v10, 0xffff0000, v10
	v_mul_f32_e32 v17, 0xbfb8aa3b, v10
	v_exp_f32_e32 v17, v17
	v_add_f32_e32 v16, 1.0, v16
	s_waitcnt lgkmcnt(0)
	v_lshlrev_b32_e32 v15, 16, v18
	v_rcp_f32_e32 v16, v16
	v_mul_f32_e32 v14, v15, v14
	v_add_f32_e32 v15, 1.0, v17
	v_rcp_f32_e32 v15, v15
	v_mul_f32_e32 v14, v16, v14
	v_and_b32_e32 v16, 0xffff0000, v18
	v_mul_f32_e32 v10, v16, v10
	v_mul_f32_e32 v10, v15, v10
	v_cvt_pk_bf16_f32 v10, v14, v10
	v_lshlrev_b32_e32 v14, 16, v11
	v_mul_f32_e32 v16, 0xbfb8aa3b, v14
	v_exp_f32_e32 v16, v16
	v_and_b32_e32 v11, 0xffff0000, v11
	v_mul_f32_e32 v17, 0xbfb8aa3b, v11
	v_exp_f32_e32 v17, v17
	v_add_f32_e32 v16, 1.0, v16
	v_lshlrev_b32_e32 v15, 16, v19
	v_rcp_f32_e32 v16, v16
	v_mul_f32_e32 v14, v15, v14
	v_add_f32_e32 v15, 1.0, v17
	v_rcp_f32_e32 v15, v15
	v_mul_f32_e32 v14, v16, v14
	v_and_b32_e32 v16, 0xffff0000, v19
	v_mul_f32_e32 v11, v16, v11
	v_mul_f32_e32 v11, v15, v11
	v_cvt_pk_bf16_f32 v11, v14, v11
	v_lshlrev_b32_e32 v14, 16, v12
	v_mul_f32_e32 v16, 0xbfb8aa3b, v14
	v_exp_f32_e32 v16, v16
	v_and_b32_e32 v12, 0xffff0000, v12
	v_mul_f32_e32 v17, 0xbfb8aa3b, v12
	v_exp_f32_e32 v17, v17
	v_add_f32_e32 v16, 1.0, v16
	v_lshlrev_b32_e32 v15, 16, v20
	v_rcp_f32_e32 v16, v16
	v_mul_f32_e32 v14, v15, v14
	v_add_f32_e32 v15, 1.0, v17
	v_rcp_f32_e32 v15, v15
	v_mul_f32_e32 v14, v16, v14
	v_and_b32_e32 v16, 0xffff0000, v20
	v_mul_f32_e32 v12, v16, v12
	v_mul_f32_e32 v12, v15, v12
	v_cvt_pk_bf16_f32 v12, v14, v12
	v_lshlrev_b32_e32 v14, 16, v13
	v_mul_f32_e32 v16, 0xbfb8aa3b, v14
	v_exp_f32_e32 v16, v16
	v_and_b32_e32 v13, 0xffff0000, v13
	v_mul_f32_e32 v17, 0xbfb8aa3b, v13
	v_exp_f32_e32 v17, v17
	v_add_f32_e32 v16, 1.0, v16
	v_lshlrev_b32_e32 v15, 16, v21
	v_rcp_f32_e32 v16, v16
	v_mul_f32_e32 v14, v15, v14
	v_add_f32_e32 v15, 1.0, v17
	v_rcp_f32_e32 v15, v15
	v_mul_f32_e32 v14, v16, v14
	v_and_b32_e32 v16, 0xffff0000, v21
	v_mul_f32_e32 v13, v16, v13
	v_mul_f32_e32 v13, v15, v13
	v_cvt_pk_bf16_f32 v13, v14, v13
	global_store_dwordx4 v[30:31], v[10:13], off nt
	ds_read_b128 v[14:17], v0 offset:6528
	s_waitcnt vmcnt(20)
; DI unsigned cvtpk(float lo, float hi) { unsigned r; asm volatile("v_cvt_pk_bf16_f32 %0, %1, %2" : "=v"(r) : "v"(lo), "v"(hi)); return r; }
; DI float bflo(unsigned w) { return __uint_as_float(w << 16); }
; DI float bfhi(unsigned w) { return __uint_as_float(w & 0xffff0000u); }
; DI float sigm(float x) { return rcpf_(1.f + ex2(-x * LOG2E)); }
; DI void attn_item(const bf16_t* __restrict__ Qw_, const bf16_t* __restrict__ Kh, const bf16_t* __restrict__ Vh, const bf16_t* Gw, bf16_t* Ow,
;                   int NT, int kt0, int qw, float sinkv, char* lds) {
;     ...
; #pragma unroll
;     for (int k = 0; k < 8; ++k) {
;         const u32x4 ov = *(const u32x4*)(OT + (er + 4 * k) * 136 + ec * 8); u32x4 w;
; #pragma unroll
;         for (int i = 0; i < 4; ++i) { const float g0 = bflo(gv[k][i]), g1 = bfhi(gv[k][i]); w[i] = cvtpk(bflo(ov[i]) * g0 * sigm(g0), bfhi(ov[i]) * g1 * sigm(g1)); }
;         __builtin_nontemporal_store(w, (u32x4*)(Ow + (size_t)(er + 4 * k) * 2048 + ec * 8));
;     }
; DI void phase_att(const Params& p, unsigned char* shm) {
;     ...
;     for (int it = blockIdx.x; it < 1024; it += gridDim.x) {
;         const int hp = it & 1, g = (it >> 1) & 3, n = it >> 3;
;         const int head = g * 4 + hp * 2 + (wid >> 2), qw = 32 * (wid & 3);
;         const int kfirst = n == 0 ? 0 : (n - 1) * 128, NT = (n == 0 || n == 127) ? 4 : 6, kt0 = kfirst - n * 128;
;         __syncthreads();
;         const size_t go = (size_t)(n * 128 + qw) * 2048 + head * 128;
;         att::attn_item(Z + (size_t)(n * 128 + qw) * 3072 + head * 128, Z + (size_t)kfirst * 3072 + 2048 + g * 128, Z + (size_t)kfirst * 3072 + 2560 + g * 128,
	v_lshlrev_b32_e32 v10, 16, v6
	v_mul_f32_e32 v12, 0xbfb8aa3b, v10
	v_exp_f32_e32 v12, v12
	v_and_b32_e32 v6, 0xffff0000, v6
	v_mul_f32_e32 v13, 0xbfb8aa3b, v6
	v_exp_f32_e32 v13, v13
	v_add_f32_e32 v12, 1.0, v12
	s_waitcnt lgkmcnt(0)
	v_lshlrev_b32_e32 v11, 16, v14
	v_rcp_f32_e32 v12, v12
	v_mul_f32_e32 v10, v11, v10
	v_add_f32_e32 v11, 1.0, v13
	v_rcp_f32_e32 v11, v11
	v_mul_f32_e32 v10, v12, v10
	v_and_b32_e32 v12, 0xffff0000, v14
	v_mul_f32_e32 v6, v12, v6
	v_mul_f32_e32 v6, v11, v6
	v_cvt_pk_bf16_f32 v6, v10, v6
	v_lshlrev_b32_e32 v10, 16, v7
	v_mul_f32_e32 v12, 0xbfb8aa3b, v10
	v_exp_f32_e32 v12, v12
	v_and_b32_e32 v7, 0xffff0000, v7
	v_mul_f32_e32 v13, 0xbfb8aa3b, v7
	v_exp_f32_e32 v13, v13
	v_add_f32_e32 v12, 1.0, v12
	v_lshlrev_b32_e32 v11, 16, v15
	v_rcp_f32_e32 v12, v12
	v_mul_f32_e32 v10, v11, v10
	v_add_f32_e32 v11, 1.0, v13
	v_rcp_f32_e32 v11, v11
	v_mul_f32_e32 v10, v12, v10
	v_and_b32_e32 v12, 0xffff0000, v15
	v_mul_f32_e32 v7, v12, v7
	v_mul_f32_e32 v7, v11, v7
	v_cvt_pk_bf16_f32 v7, v10, v7
	v_lshlrev_b32_e32 v10, 16, v8
	v_mul_f32_e32 v12, 0xbfb8aa3b, v10
	v_exp_f32_e32 v12, v12
	v_and_b32_e32 v8, 0xffff0000, v8
	v_mul_f32_e32 v13, 0xbfb8aa3b, v8
	v_exp_f32_e32 v13, v13
	v_add_f32_e32 v12, 1.0, v12
	v_lshlrev_b32_e32 v11, 16, v16
	v_rcp_f32_e32 v12, v12
	v_mul_f32_e32 v10, v11, v10
	v_add_f32_e32 v11, 1.0, v13
	v_rcp_f32_e32 v11, v11
	v_mul_f32_e32 v10, v12, v10
	v_and_b32_e32 v12, 0xffff0000, v16
	v_mul_f32_e32 v8, v12, v8
	v_mul_f32_e32 v8, v11, v8
	v_cvt_pk_bf16_f32 v8, v10, v8
	v_lshlrev_b32_e32 v10, 16, v9
	v_mul_f32_e32 v12, 0xbfb8aa3b, v10
	v_exp_f32_e32 v12, v12
	v_and_b32_e32 v9, 0xffff0000, v9
	v_mul_f32_e32 v13, 0xbfb8aa3b, v9
	v_exp_f32_e32 v13, v13
	v_add_f32_e32 v12, 1.0, v12
	v_lshlrev_b32_e32 v11, 16, v17
	v_rcp_f32_e32 v12, v12
	v_mul_f32_e32 v10, v11, v10
	v_add_f32_e32 v11, 1.0, v13
	v_rcp_f32_e32 v11, v11
	v_mul_f32_e32 v10, v12, v10
	v_and_b32_e32 v12, 0xffff0000, v17
	v_mul_f32_e32 v9, v12, v9
	v_mul_f32_e32 v9, v11, v9
	v_cvt_pk_bf16_f32 v9, v10, v9
	ds_read_b128 v[10:13], v0 offset:7616
	s_waitcnt vmcnt(19)
	v_lshlrev_b32_e32 v0, 16, v2
	global_store_dwordx4 v[28:29], v[6:9], off nt
	v_and_b32_e32 v2, 0xffff0000, v2
	s_nop 0
	v_mul_f32_e32 v7, 0xbfb8aa3b, v0
	v_exp_f32_e32 v7, v7
	v_mul_f32_e32 v8, 0xbfb8aa3b, v2
	v_exp_f32_e32 v8, v8
	s_waitcnt lgkmcnt(0)
	v_lshlrev_b32_e32 v6, 16, v10
	v_add_f32_e32 v7, 1.0, v7
	v_rcp_f32_e32 v7, v7
	v_mul_f32_e32 v0, v6, v0
	v_add_f32_e32 v6, 1.0, v8
	v_rcp_f32_e32 v6, v6
	v_mul_f32_e32 v0, v7, v0
	v_and_b32_e32 v7, 0xffff0000, v10
	v_mul_f32_e32 v2, v7, v2
	v_mul_f32_e32 v2, v6, v2
	v_cvt_pk_bf16_f32 v2, v0, v2
	v_lshlrev_b32_e32 v0, 16, v3
	v_mul_f32_e32 v7, 0xbfb8aa3b, v0
	v_exp_f32_e32 v7, v7
	v_and_b32_e32 v3, 0xffff0000, v3
	v_mul_f32_e32 v8, 0xbfb8aa3b, v3
	v_exp_f32_e32 v8, v8
	v_add_f32_e32 v7, 1.0, v7
	v_lshlrev_b32_e32 v6, 16, v11
	v_rcp_f32_e32 v7, v7
	v_mul_f32_e32 v0, v6, v0
	v_add_f32_e32 v6, 1.0, v8
	v_rcp_f32_e32 v6, v6
	v_mul_f32_e32 v0, v7, v0
	v_and_b32_e32 v7, 0xffff0000, v11
	v_mul_f32_e32 v3, v7, v3
	v_mul_f32_e32 v3, v6, v3
	v_cvt_pk_bf16_f32 v3, v0, v3
	v_lshlrev_b32_e32 v0, 16, v4
	v_mul_f32_e32 v7, 0xbfb8aa3b, v0
	v_exp_f32_e32 v7, v7
	v_and_b32_e32 v4, 0xffff0000, v4
	v_mul_f32_e32 v8, 0xbfb8aa3b, v4
	v_exp_f32_e32 v8, v8
	v_add_f32_e32 v7, 1.0, v7
	v_lshlrev_b32_e32 v6, 16, v12
	v_rcp_f32_e32 v7, v7
	v_mul_f32_e32 v0, v6, v0
	v_add_f32_e32 v6, 1.0, v8
	v_rcp_f32_e32 v6, v6
	v_mul_f32_e32 v0, v7, v0
	v_and_b32_e32 v7, 0xffff0000, v12
	v_mul_f32_e32 v4, v7, v4
	v_mul_f32_e32 v4, v6, v4
	v_cvt_pk_bf16_f32 v4, v0, v4
	v_lshlrev_b32_e32 v0, 16, v5
	v_mul_f32_e32 v7, 0xbfb8aa3b, v0
	v_exp_f32_e32 v7, v7
	v_and_b32_e32 v5, 0xffff0000, v5
	v_mul_f32_e32 v8, 0xbfb8aa3b, v5
	v_exp_f32_e32 v8, v8
	v_add_f32_e32 v7, 1.0, v7
	v_lshlrev_b32_e32 v6, 16, v13
	v_rcp_f32_e32 v7, v7
	v_mul_f32_e32 v0, v6, v0
	v_add_f32_e32 v6, 1.0, v8
	v_rcp_f32_e32 v6, v6
	v_mul_f32_e32 v0, v7, v0
	v_and_b32_e32 v7, 0xffff0000, v13
	v_mul_f32_e32 v5, v7, v5
	v_mul_f32_e32 v5, v6, v5
	v_cvt_pk_bf16_f32 v5, v0, v5
	global_store_dwordx4 v[26:27], v[2:5], off nt
	s_cbranch_scc0 .LBB0_265
.LBB0_238:
	s_lshl_b32 s5, s51, 1
	s_bfe_u32 s15, s51, 0x20001
	s_ashr_i32 s54, s51, 3
	s_and_b32 s5, s5, 2
	s_lshl_b32 s4, s15, 2
	s_add_i32 s17, s5, s31
	s_lshl_b32 s58, s54, 7
	s_add_i32 s17, s17, s4
	s_add_i32 s14, s58, 0xffffff80
	s_cmp_lt_u32 s51, 8
	s_cselect_b64 s[20:21], -1, 0
	s_and_b64 s[4:5], s[20:21], exec
	s_cselect_b32 s16, 0, s14
	s_or_b32 s14, s58, s34
	s_sub_i32 s55, s16, s58
	s_mul_i32 s5, s14, 0x1800
	s_mul_hi_i32 s4, s14, 0x1800
	s_add_u32 s5, s11, s5
	s_addc_u32 s4, s22, s4
	s_lshl_b32 s18, s17, 8
	s_add_u32 s52, s5, s18
	s_addc_u32 s53, s4, 0
	s_mul_i32 s5, s16, 0x1800
	s_mul_hi_i32 s4, s16, 0x1800
	s_add_u32 s5, s11, s5
	s_addc_u32 s4, s22, s4
	s_lshl_b32 s15, s15, 8
	s_add_u32 s15, s5, s15
	s_addc_u32 s19, s4, 0
	s_add_u32 s4, s15, 0x1000
	s_addc_u32 s5, s19, 0
	s_add_u32 s18, s15, 0x1400
	s_addc_u32 s19, s19, 0
	s_barrier
	s_cmp_eq_u32 s74, 1
	s_cbranch_scc0 .Latt_load_now
	s_waitcnt vmcnt(8)
	v_mov_b64_e32 v[2:3], v[130:131]
	v_mov_b64_e32 v[4:5], v[132:133]
	v_mov_b64_e32 v[6:7], v[134:135]
	v_mov_b64_e32 v[8:9], v[136:137]
	v_mov_b64_e32 v[10:11], v[138:139]
	v_mov_b64_e32 v[12:13], v[140:141]
	v_mov_b64_e32 v[14:15], v[142:143]
	v_mov_b64_e32 v[16:17], v[144:145]
	v_mov_b32_e32 v0, v62
	s_branch .Latt_loaded
; DI int v_st(int k, int c) { const int kk = (k & ~0xC) | ((k & 4) << 1) | ((k & 8) >> 1); return ((kk >> 3) * 4 + (c >> 5)) * 512 + ((kk & 7) * 32 + (c & 31)) * 2; }
; DI int v_rd_base(int lane) { return ((lane & 3) << 3) | (((lane >> 2) & 3) << 6) | (((lane >> 4) & 1) << 5) | (((lane >> 5) & 1) << 8); }
; DI void attn_item(const bf16_t* __restrict__ Qw_, const bf16_t* __restrict__ Kh, const bf16_t* __restrict__ Vh, const bf16_t* Gw, bf16_t* Ow,
;                   int NT, int kt0, int qw, float sinkv, char* lds) {
;     ...
;     const bf16_t* Qw = Qw_ + (size_t)r32 * LDK + hi * 8;
; #pragma unroll
;     for (int d0 = 0; d0 < 8; ++d0) qr[d0] = *(const bf16x8*)(Qw + d0 * 16);
;     const int sr = tid >> 4, sc = (tid & 15) * 8, vst0 = v_st(sr, sc), vst1 = v_st(32 + sr, sc);
;     const int vb0 = (int)(uintptr_t)V_lds + v_rd_base(lane);
;     struct { bf16x8 vs0, vs1, ks0, ks1; } sr_[2];
.Latt_load_now:
	global_load_dwordx4 v[2:5], v200, s[18:19]
	global_load_dwordx4 v[6:9], v201, s[18:19]
	global_load_dwordx4 v[10:13], v200, s[4:5]
	global_load_dwordx4 v[14:17], v201, s[4:5]
	v_lshl_add_u64 v[18:19], s[52:53], 0, v[178:179]
	v_lshl_add_u64 v[18:19], v[18:19], 0, v[184:185]
	global_load_dwordx4 v[126:129], v[18:19], off
	global_load_dwordx4 v[122:125], v[18:19], off offset:32
	global_load_dwordx4 v[118:121], v[18:19], off offset:64
	global_load_dwordx4 v[114:117], v[18:19], off offset:96
	global_load_dwordx4 v[110:113], v[18:19], off offset:128
	global_load_dwordx4 v[106:109], v[18:19], off offset:160
	global_load_dwordx4 v[102:105], v[18:19], off offset:192
	global_load_dwordx4 v[98:101], v[18:19], off offset:224
	s_lshl_b32 s15, s17, 2
	v_mov_b32_e32 v0, s15
	global_load_dword v0, v0, s[8:9]
	s_waitcnt vmcnt(0)
; DI void maskT(f32x16& p0, f32x16& p1, int kt, int qw, int r32, int hi) {
;     if ((kt - qw - 31 < -128) || (kt + 63 - qw > 128)) {
;         const int db = kt - (qw + r32) + 4 * hi;
; #pragma unroll
;         for (int r = 0; r < 16; ++r) { const int d = db + (r & 3) + 8 * (r >> 2);
;             p0[r] = (d >= -128 && d <= 128) ? p0[r] : -1e30f; p1[r] = (d + 32 >= -128 && d + 32 <= 128) ? p1[r] : -1e30f; }
;     }
; }
; DI void qkt(f32x16& p0, f32x16& p1, const char* Ks, const bf16x8* qr, int r32, int hi) {
; #pragma unroll
;     for (int i = 0; i < 16; ++i) { p0[i] = 0.f; p1[i] = 0.f; }
; #pragma unroll
;     for (int d0 = 0; d0 < 8; ++d0) { const int cb = (d0 * 16 + hi * 8) * 2;
;         const bf16x8 b0 = *reinterpret_cast<const bf16x8*>(Ks + KSWZ(r32, cb));
;         const bf16x8 b1 = *reinterpret_cast<const bf16x8*>(Ks + KSWZ(32 + r32, cb));
;         p0 = __builtin_amdgcn_mfma_f32_32x32x16_bf16(b0, qr[d0], p0, 0, 0, 0);
;         p1 = __builtin_amdgcn_mfma_f32_32x32x16_bf16(b1, qr[d0], p1, 0, 0, 0); }
; }
.Latt_loaded:
	s_cmp_lt_i32 s55, s37
	s_cselect_b64 s[56:57], -1, 0
	s_sub_i32 s15, s55, s34
	s_add_i32 s15, s15, 63
	s_cmpk_gt_i32 s15, 0x80
	s_cselect_b64 s[60:61], -1, 0
	s_or_b64 s[56:57], s[56:57], s[60:61]
	v_readfirstlane_b32 s52, v202
	s_andn2_b64 vcc, exec, s[56:57]
	s_waitcnt vmcnt(12)
	ds_write_b128 v208, v[2:5]
	s_waitcnt vmcnt(11)
	ds_write_b128 v209, v[6:9]
	s_waitcnt vmcnt(10)
	ds_write_b128 v210, v[10:13] offset:32768
	s_waitcnt vmcnt(9)
	ds_write_b128 v211, v[14:17] offset:32768
	s_waitcnt lgkmcnt(0)
	s_barrier
	ds_read_b128 v[2:5], v212 offset:32768
	ds_read_b128 v[6:9], v212 offset:40960
	s_waitcnt vmcnt(8) lgkmcnt(1)
	v_mfma_f32_32x32x16_bf16 v[18:33], v[2:5], v[126:129], 0
	ds_read_b128 v[34:37], v213 offset:32768
	ds_read_b128 v[38:41], v213 offset:40960
	s_waitcnt lgkmcnt(2)
	v_mfma_f32_32x32x16_bf16 v[2:17], v[6:9], v[126:129], 0
	s_waitcnt vmcnt(7) lgkmcnt(1)
	v_mfma_f32_32x32x16_bf16 v[18:33], v[34:37], v[122:125], v[18:33]
	s_waitcnt lgkmcnt(0)
	v_mfma_f32_32x32x16_bf16 v[2:17], v[38:41], v[122:125], v[2:17]
	ds_read_b128 v[34:37], v214 offset:32768
	ds_read_b128 v[38:41], v214 offset:40960
	s_waitcnt vmcnt(6) lgkmcnt(1)
	v_mfma_f32_32x32x16_bf16 v[18:33], v[34:37], v[118:121], v[18:33]
	s_waitcnt lgkmcnt(0)
	v_mfma_f32_32x32x16_bf16 v[2:17], v[38:41], v[118:121], v[2:17]
	ds_read_b128 v[34:37], v215 offset:32768
	ds_read_b128 v[38:41], v215 offset:40960
	s_waitcnt vmcnt(5) lgkmcnt(1)
	v_mfma_f32_32x32x16_bf16 v[18:33], v[34:37], v[114:117], v[18:33]
	s_waitcnt lgkmcnt(0)
	v_mfma_f32_32x32x16_bf16 v[2:17], v[38:41], v[114:117], v[2:17]
	ds_read_b128 v[34:37], v216 offset:32768
	ds_read_b128 v[38:41], v216 offset:40960
	s_waitcnt vmcnt(4) lgkmcnt(1)
	v_mfma_f32_32x32x16_bf16 v[18:33], v[34:37], v[110:113], v[18:33]
	s_waitcnt lgkmcnt(0)
	v_mfma_f32_32x32x16_bf16 v[2:17], v[38:41], v[110:113], v[2:17]
	ds_read_b128 v[34:37], v217 offset:32768
	ds_read_b128 v[38:41], v217 offset:40960
	s_waitcnt vmcnt(3) lgkmcnt(1)
	v_mfma_f32_32x32x16_bf16 v[18:33], v[34:37], v[106:109], v[18:33]
	s_waitcnt lgkmcnt(0)
	v_mfma_f32_32x32x16_bf16 v[2:17], v[38:41], v[106:109], v[2:17]
	ds_read_b128 v[34:37], v218 offset:32768
	ds_read_b128 v[38:41], v218 offset:40960
	s_waitcnt vmcnt(2) lgkmcnt(1)
	v_mfma_f32_32x32x16_bf16 v[18:33], v[34:37], v[102:105], v[18:33]
	ds_read_b128 v[34:37], v219 offset:32768
	s_waitcnt lgkmcnt(1)
	v_mfma_f32_32x32x16_bf16 v[2:17], v[38:41], v[102:105], v[2:17]
	ds_read_b128 v[38:41], v219 offset:40960
	s_waitcnt vmcnt(1) lgkmcnt(1)
	v_mfma_f32_32x32x16_bf16 v[18:33], v[34:37], v[98:101], v[18:33]
	s_waitcnt lgkmcnt(0)
	v_mfma_f32_32x32x16_bf16 v[2:17], v[38:41], v[98:101], v[2:17]
	s_cbranch_vccnz .LBB0_240
	v_or_b32_e32 v34, s55, v193
	v_sub_u32_e32 v34, v34, v192
	v_add_u32_e32 v35, 0x80, v34
	v_cmp_gt_u32_e32 vcc, s41, v35
	v_add_u32_e32 v35, 0xa0, v34
	s_nop 3
	v_cndmask_b32_e32 v18, v220, v18, vcc
	v_cmp_gt_u32_e32 vcc, s41, v35
	v_add_u32_e32 v35, 0x81, v34
	s_nop 0
	v_cndmask_b32_e32 v2, v220, v2, vcc
	v_cmp_gt_u32_e32 vcc, s41, v35
	v_add_u32_e32 v35, 0xa1, v34
	s_nop 0
	v_cndmask_b32_e32 v19, v220, v19, vcc
	v_cmp_gt_u32_e32 vcc, s41, v35
	v_add_u32_e32 v35, 0x82, v34
	s_nop 0
	v_cndmask_b32_e32 v3, v220, v3, vcc
	v_cmp_gt_u32_e32 vcc, s41, v35
	v_add_u32_e32 v35, 0xa2, v34
	s_nop 0
	v_cndmask_b32_e32 v20, v220, v20, vcc
	v_cmp_gt_u32_e32 vcc, s41, v35
	v_add_u32_e32 v35, 0x83, v34
	s_nop 0
	v_cndmask_b32_e32 v4, v220, v4, vcc
	v_cmp_gt_u32_e32 vcc, s41, v35
	v_add_u32_e32 v35, 0xa3, v34
	s_nop 0
	v_cndmask_b32_e32 v21, v220, v21, vcc
	v_cmp_gt_u32_e32 vcc, s41, v35
	v_add_u32_e32 v35, 0x88, v34
	s_nop 0
	v_cndmask_b32_e32 v5, v220, v5, vcc
	v_cmp_gt_u32_e32 vcc, s41, v35
	v_add_u32_e32 v35, 0xa8, v34
	s_nop 0
	v_cndmask_b32_e32 v22, v220, v22, vcc
	v_cmp_gt_u32_e32 vcc, s41, v35
	v_add_u32_e32 v35, 0x89, v34
	s_nop 0
	v_cndmask_b32_e32 v6, v220, v6, vcc
	v_cmp_gt_u32_e32 vcc, s41, v35
	v_add_u32_e32 v35, 0xa9, v34
	s_nop 0
	v_cndmask_b32_e32 v23, v220, v23, vcc
	v_cmp_gt_u32_e32 vcc, s41, v35
	v_add_u32_e32 v35, 0x8a, v34
	s_nop 0
	v_cndmask_b32_e32 v7, v220, v7, vcc
	v_cmp_gt_u32_e32 vcc, s41, v35
	v_add_u32_e32 v35, 0xaa, v34
	s_nop 0
	v_cndmask_b32_e32 v24, v220, v24, vcc
	v_cmp_gt_u32_e32 vcc, s41, v35
	v_add_u32_e32 v35, 0x8b, v34
	s_nop 0
	v_cndmask_b32_e32 v8, v220, v8, vcc
	v_cmp_gt_u32_e32 vcc, s41, v35
	v_add_u32_e32 v35, 0xab, v34
	s_nop 0
	v_cndmask_b32_e32 v25, v220, v25, vcc
	v_cmp_gt_u32_e32 vcc, s41, v35
	v_add_u32_e32 v35, 0x90, v34
	s_nop 0
	v_cndmask_b32_e32 v9, v220, v9, vcc
	v_cmp_gt_u32_e32 vcc, s41, v35
	v_add_u32_e32 v35, 0xb0, v34
	s_nop 0
	v_cndmask_b32_e32 v26, v220, v26, vcc
	v_cmp_gt_u32_e32 vcc, s41, v35
	v_add_u32_e32 v35, 0x91, v34
	s_nop 0
	v_cndmask_b32_e32 v10, v220, v10, vcc
	v_cmp_gt_u32_e32 vcc, s41, v35
	v_add_u32_e32 v35, 0xb1, v34
	s_nop 0
	v_cndmask_b32_e32 v27, v220, v27, vcc
	v_cmp_gt_u32_e32 vcc, s41, v35
	v_add_u32_e32 v35, 0x92, v34
	s_nop 0
	v_cndmask_b32_e32 v11, v220, v11, vcc
	v_cmp_gt_u32_e32 vcc, s41, v35
	v_add_u32_e32 v35, 0xb2, v34
	s_nop 0
	v_cndmask_b32_e32 v28, v220, v28, vcc
	v_cmp_gt_u32_e32 vcc, s41, v35
	v_add_u32_e32 v35, 0x93, v34
	s_nop 0
	v_cndmask_b32_e32 v12, v220, v12, vcc
	v_cmp_gt_u32_e32 vcc, s41, v35
	v_add_u32_e32 v35, 0xb3, v34
	s_nop 0
	v_cndmask_b32_e32 v29, v220, v29, vcc
	v_cmp_gt_u32_e32 vcc, s41, v35
	v_add_u32_e32 v35, 0x98, v34
	s_nop 0
	v_cndmask_b32_e32 v13, v220, v13, vcc
	v_cmp_gt_u32_e32 vcc, s41, v35
	v_add_u32_e32 v35, 0xb8, v34
	s_nop 0
	v_cndmask_b32_e32 v30, v220, v30, vcc
	v_cmp_gt_u32_e32 vcc, s41, v35
	v_add_u32_e32 v35, 0x99, v34
	s_nop 0
	v_cndmask_b32_e32 v14, v220, v14, vcc
	v_cmp_gt_u32_e32 vcc, s41, v35
	v_add_u32_e32 v35, 0xb9, v34
	s_nop 0
	v_cndmask_b32_e32 v31, v220, v31, vcc
	v_cmp_gt_u32_e32 vcc, s41, v35
	v_add_u32_e32 v35, 0x9a, v34
	s_nop 0
	v_cndmask_b32_e32 v15, v220, v15, vcc
	v_cmp_gt_u32_e32 vcc, s41, v35
	v_add_u32_e32 v35, 0xba, v34
	s_nop 0
	v_cndmask_b32_e32 v32, v220, v32, vcc
	v_cmp_gt_u32_e32 vcc, s41, v35
	v_add_u32_e32 v35, 0x9b, v34
	v_add_u32_e32 v34, 0xbb, v34
	v_cndmask_b32_e32 v16, v220, v16, vcc
	v_cmp_gt_u32_e32 vcc, s41, v35
	s_nop 1
	v_cndmask_b32_e32 v33, v220, v33, vcc
	v_cmp_gt_u32_e32 vcc, s41, v34
	s_nop 1
	v_cndmask_b32_e32 v17, v220, v17, vcc
